# same LDS-traffic-halving fragment mapping in the P3, P4 and P6 small-tile GEMMs (on v48)
# baseline (speedup 1.0000x reference)
; #define LAS __attribute__((address_space(3)))
; #define SG_LOAD(kc, sg) do { _Pragma("unroll") for (int i_ = 0; i_ < 4; ++i_) { const int idx_ = tid + 512 * i_; \
;             ra[sg][i_] = *(const u32x4*)(A + (size_t)(row0 + (idx_ >> 5)) * ld + (kc) * 256 + (idx_ & 31) * 8); if (NC == 64 || i_ < 2) rb[sg][i_] = *(const u32x4*)(Bt + (size_t)(col0 + (idx_ >> 5)) * ld + (kc) * 256 + (idx_ & 31) * 8); } } while (0)
; template <int NC, class Epi>
; __device__ __forceinline__ void small_gemm_phase(LAS unsigned char* lds, const bf16_t* A, const bf16_t* Bt, int K, int ld, int ncolt  , const Epi& E, int first, int nblk, int bid, int tid) {
;     ...
;     for (int u = ub; u < 8 * ncolt; u += nblk) {
;         const int rt = u & 7, ct = u >> 3;
;         const int row0 = NPT + 64 * rt, col0 = NC * ct;
;         u32x4 ra[2][4], rb[2][4];
;     ...
;         SG_LOAD(0, 0); SG_LOAD(1, 1);
;         f32x4 acc0 = {0.f, 0.f, 0.f, 0.f}, acc1 = {0.f, 0.f, 0.f, 0.f};
;         const LAS unsigned char* apl = lds + (16 * mt + fr) * SG_STRIDE + 16 * fq;
;         const LAS unsigned char* bpl = lds + SG_BOFF + ((NC / 2) * nh + fr) * SG_STRIDE + 16 * fq;
; #pragma unroll 1
;         for (int kc = 0; kc < nch; kc += 2) { SG_STEP(kc, 0); SG_STEP(kc + 1, 1); }
.LBB0_720:
	s_lshl_b32 s8, s5, 6
	s_and_b32 s11, s8, 0x1c0
	s_bitset1_b32 s11, 14
	s_lshl_b32 s8, s5, 2
	v_or_b32_e32 v0, s11, v148
	s_and_b32 s10, s8, 0x7fffffe0
	v_lshlrev_b32_e32 v52, 11, v0
	v_lshl_add_u64 v[58:59], v[54:55], 0, v[52:53]
	v_or_b32_e32 v52, s10, v148
	v_lshlrev_b64 v[0:1], 11, v[52:53]
	v_lshl_add_u64 v[60:61], v[56:57], 0, v[0:1]
	v_or_b32_e32 v0, s11, v79
	v_lshlrev_b32_e32 v52, 11, v0
	v_lshl_add_u64 v[62:63], v[54:55], 0, v[52:53]
	v_add_u32_e32 v52, s10, v79
	v_lshlrev_b64 v[0:1], 11, v[52:53]
	v_lshl_add_u64 v[64:65], v[56:57], 0, v[0:1]
	v_or_b32_e32 v0, s11, v80
	v_lshlrev_b32_e32 v52, 11, v0
	v_lshl_add_u64 v[66:67], v[54:55], 0, v[52:53]
	v_add_lshl_u32 v52, s11, v81, 11
	v_lshl_add_u64 v[68:69], v[54:55], 0, v[52:53]
	s_waitcnt lgkmcnt(0)
	global_load_dwordx4 v[0:3], v[58:59], off
	global_load_dwordx4 v[4:7], v[58:59], off offset:512
	global_load_dwordx4 v[8:11], v[60:61], off
	global_load_dwordx4 v[12:15], v[60:61], off offset:512
	global_load_dwordx4 v[16:19], v[62:63], off
	global_load_dwordx4 v[20:23], v[62:63], off offset:512
	global_load_dwordx4 v[24:27], v[64:65], off
	global_load_dwordx4 v[28:31], v[64:65], off offset:512
	global_load_dwordx4 v[32:35], v[66:67], off
	global_load_dwordx4 v[36:39], v[66:67], off offset:512
	global_load_dwordx4 v[40:43], v[68:69], off
	global_load_dwordx4 v[44:47], v[68:69], off offset:512
	s_mov_b64 s[8:9], -1
	v_mov_b32_e32 v48, 0
	v_mov_b32_e32 v49, v53
	v_mov_b32_e32 v50, v53
	v_mov_b32_e32 v51, v53
	v_and_b32_e32 v138, 15, v192
	v_mul_u32_u24_e32 v138, 0x210, v138
	v_bfe_u32 v139, v192, 4, 2
	v_lshl_add_u32 v138, v139, 4, v138
	v_lshrrev_b32_e32 v139, 6, v192
	v_lshl_add_u32 v138, v139, 6, v138
	v_add_u32_e32 v139, 0x10800, v138
	v_mov_b32_e32 v106, 0
	v_mov_b32_e32 v107, 0
	v_mov_b32_e32 v108, 0
	v_mov_b32_e32 v109, 0
	v_mov_b32_e32 v110, 0
	v_mov_b32_e32 v111, 0
	v_mov_b32_e32 v112, 0
	v_mov_b32_e32 v113, 0
	v_mov_b32_e32 v114, 0
	v_mov_b32_e32 v115, 0
	v_mov_b32_e32 v116, 0
	v_mov_b32_e32 v117, 0
	v_mov_b32_e32 v118, 0
	v_mov_b32_e32 v119, 0
	v_mov_b32_e32 v120, 0
	v_mov_b32_e32 v121, 0
	v_mov_b32_e32 v122, 0
	v_mov_b32_e32 v123, 0
	v_mov_b32_e32 v124, 0
	v_mov_b32_e32 v125, 0
	v_mov_b32_e32 v126, 0
	v_mov_b32_e32 v127, 0
	v_mov_b32_e32 v128, 0
	v_mov_b32_e32 v129, 0
	v_mov_b32_e32 v130, 0
	v_mov_b32_e32 v131, 0
	v_mov_b32_e32 v132, 0
	v_mov_b32_e32 v133, 0
	v_mov_b32_e32 v134, 0
	v_mov_b32_e32 v135, 0
	v_mov_b32_e32 v136, 0
	v_mov_b32_e32 v137, 0
	s_branch .LBB0_722
.LBB0_721:
	s_waitcnt lgkmcnt(0)
	s_barrier
	ds_read_b128 v[194:197], v139
	ds_read_b128 v[198:201], v139 offset:8448
	ds_read_b128 v[202:205], v139 offset:16896
	ds_read_b128 v[206:209], v139 offset:25344
	ds_read_b128 v[210:213], v139 offset:33792
	ds_read_b128 v[214:217], v139 offset:42240
	s_waitcnt lgkmcnt(0)
	v_mfma_f32_16x16x32_bf16 v[106:109], v[210:213], v[194:197], v[106:109]
	v_mfma_f32_16x16x32_bf16 v[110:113], v[214:217], v[194:197], v[110:113]
	v_mfma_f32_16x16x32_bf16 v[114:117], v[210:213], v[198:201], v[114:117]
	v_mfma_f32_16x16x32_bf16 v[118:121], v[214:217], v[198:201], v[118:121]
	v_mfma_f32_16x16x32_bf16 v[122:125], v[210:213], v[202:205], v[122:125]
	v_mfma_f32_16x16x32_bf16 v[126:129], v[214:217], v[202:205], v[126:129]
	v_mfma_f32_16x16x32_bf16 v[130:133], v[210:213], v[206:209], v[130:133]
	v_mfma_f32_16x16x32_bf16 v[134:137], v[214:217], v[206:209], v[134:137]
	s_xor_b64 s[12:13], s[8:9], -1
	s_mov_b64 s[8:9], 0
	s_and_b64 vcc, exec, s[12:13]
	s_cbranch_vccnz .Lsk_p3_reduce

; #define LAS __attribute__((address_space(3)))
; #define SG_LOAD(kc, sg) do { _Pragma("unroll") for (int i_ = 0; i_ < 4; ++i_) { const int idx_ = tid + 512 * i_; \
;             ra[sg][i_] = *(const u32x4*)(A + (size_t)(row0 + (idx_ >> 5)) * ld + (kc) * 256 + (idx_ & 31) * 8); if (NC == 64 || i_ < 2) rb[sg][i_] = *(const u32x4*)(Bt + (size_t)(col0 + (idx_ >> 5)) * ld + (kc) * 256 + (idx_ & 31) * 8); } } while (0)
; template <int NC, class Epi>
; __device__ __forceinline__ void small_gemm_phase(LAS unsigned char* lds, const bf16_t* A, const bf16_t* Bt, int K, int ld, int ncolt  , const Epi& E, int first, int nblk, int bid, int tid) {
;     ...
;         SG_LOAD(0, 0); SG_LOAD(1, 1);
;         f32x4 acc0 = {0.f, 0.f, 0.f, 0.f}, acc1 = {0.f, 0.f, 0.f, 0.f};
;         const LAS unsigned char* apl = lds + (16 * mt + fr) * SG_STRIDE + 16 * fq;
;         const LAS unsigned char* bpl = lds + SG_BOFF + ((NC / 2) * nh + fr) * SG_STRIDE + 16 * fq;
; #pragma unroll 1
;         for (int kc = 0; kc < nch; kc += 2) { SG_STEP(kc, 0); SG_STEP(kc + 1, 1); }
;     ...
;         E(row0 + 16 * mt + fr, col0 + (NC / 2) * nh, fq, acc0, acc1, NC == 64 ? 2 : 1);
.LBB0_724:
	s_waitcnt lgkmcnt(0)
	s_barrier
	ds_read_b128 v[194:197], v138
	ds_read_b128 v[198:201], v138 offset:8448
	ds_read_b128 v[202:205], v138 offset:16896
	ds_read_b128 v[206:209], v138 offset:25344
	ds_read_b128 v[210:213], v138 offset:33792
	ds_read_b128 v[214:217], v138 offset:42240
	s_waitcnt lgkmcnt(0)
	v_mfma_f32_16x16x32_bf16 v[106:109], v[210:213], v[194:197], v[106:109]
	v_mfma_f32_16x16x32_bf16 v[110:113], v[214:217], v[194:197], v[110:113]
	v_mfma_f32_16x16x32_bf16 v[114:117], v[210:213], v[198:201], v[114:117]
	v_mfma_f32_16x16x32_bf16 v[118:121], v[214:217], v[198:201], v[118:121]
	v_mfma_f32_16x16x32_bf16 v[122:125], v[210:213], v[202:205], v[122:125]
	v_mfma_f32_16x16x32_bf16 v[126:129], v[214:217], v[202:205], v[126:129]
	v_mfma_f32_16x16x32_bf16 v[130:133], v[210:213], v[206:209], v[130:133]
	v_mfma_f32_16x16x32_bf16 v[134:137], v[214:217], v[206:209], v[134:137]
	v_add_u32_e32 v52, v74, v82
	s_andn2_b64 vcc, exec, s[8:9]
	ds_write_b128 v52, v[4:7]
	v_add_u32_e32 v104, v75, v82
	ds_write_b128 v104, v[12:15]
	v_add_u32_e32 v104, v74, v83
	ds_write_b128 v104, v[20:23]
	v_add_u32_e32 v104, v75, v83
	ds_write_b128 v104, v[28:31]
	ds_write_b128 v52, v[36:39] offset:16896
	v_add_u32_e32 v52, v74, v84
	s_waitcnt vmcnt(0)
	ds_write_b128 v52, v[44:47]
	s_cbranch_vccnz .LBB0_721
	global_load_dwordx4 v[4:7], v[58:59], off offset:1536
	global_load_dwordx4 v[12:15], v[60:61], off offset:1536
	global_load_dwordx4 v[20:23], v[62:63], off offset:1536
	global_load_dwordx4 v[28:31], v[64:65], off offset:1536
	global_load_dwordx4 v[36:39], v[66:67], off offset:1536
	global_load_dwordx4 v[44:47], v[68:69], off offset:1536
	s_branch .LBB0_721
.Lsk_p3_reduce:
	s_nop 15
	s_nop 15
	s_waitcnt lgkmcnt(0)
	s_barrier
	v_lshlrev_b32_e32 v140, 4, v192
	v_lshrrev_b32_e32 v141, 6, v192
	v_mul_u32_u24_e32 v141, 0x1c00, v141
	v_add_u32_e32 v141, v140, v141
	ds_write_b128 v141, v[106:109]
	ds_write_b128 v141, v[110:113] offset:1024
	ds_write_b128 v141, v[114:117] offset:2048
	ds_write_b128 v141, v[118:121] offset:3072
	ds_write_b128 v141, v[122:125] offset:4096
	ds_write_b128 v141, v[126:129] offset:5120
	ds_write_b128 v141, v[130:133] offset:6144
	ds_write_b128 v141, v[134:137] offset:7168
	s_waitcnt lgkmcnt(0)
	s_barrier
	ds_read_b128 v[194:197], v140
	ds_read_b128 v[198:201], v140 offset:8192
	ds_read_b128 v[202:205], v140 offset:16384
	ds_read_b128 v[206:209], v140 offset:24576
	ds_read_b128 v[210:213], v140 offset:32768
	ds_read_b128 v[214:217], v140 offset:40960
	ds_read_b128 v[218:221], v140 offset:49152
	ds_read_b128 v[222:225], v140 offset:57344
	s_waitcnt lgkmcnt(6)
	v_pk_add_f32 v[48:49], v[194:195], v[198:199]
	v_pk_add_f32 v[50:51], v[196:197], v[200:201]
	s_waitcnt lgkmcnt(5)
	v_pk_add_f32 v[48:49], v[48:49], v[202:203]
	v_pk_add_f32 v[50:51], v[50:51], v[204:205]
	s_waitcnt lgkmcnt(4)
	v_pk_add_f32 v[48:49], v[48:49], v[206:207]
	v_pk_add_f32 v[50:51], v[50:51], v[208:209]
	s_waitcnt lgkmcnt(3)
	v_pk_add_f32 v[48:49], v[48:49], v[210:211]
	v_pk_add_f32 v[50:51], v[50:51], v[212:213]
	s_waitcnt lgkmcnt(2)
	v_pk_add_f32 v[48:49], v[48:49], v[214:215]
	v_pk_add_f32 v[50:51], v[50:51], v[216:217]
	s_waitcnt lgkmcnt(1)
	v_pk_add_f32 v[48:49], v[48:49], v[218:219]
	v_pk_add_f32 v[50:51], v[50:51], v[220:221]
	s_waitcnt lgkmcnt(0)
	v_pk_add_f32 v[48:49], v[48:49], v[222:223]
	v_pk_add_f32 v[50:51], v[50:51], v[224:225]
	s_barrier
	s_branch .LBB0_726

; #define LAS __attribute__((address_space(3)))
; #define SG_LOAD(kc, sg) do { _Pragma("unroll") for (int i_ = 0; i_ < 4; ++i_) { const int idx_ = tid + 512 * i_; \
;             ra[sg][i_] = *(const u32x4*)(A + (size_t)(row0 + (idx_ >> 5)) * ld + (kc) * 256 + (idx_ & 31) * 8); if (NC == 64 || i_ < 2) rb[sg][i_] = *(const u32x4*)(Bt + (size_t)(col0 + (idx_ >> 5)) * ld + (kc) * 256 + (idx_ & 31) * 8); } } while (0)
; template <int NC, class Epi>
; __device__ __forceinline__ void small_gemm_phase(LAS unsigned char* lds, const bf16_t* A, const bf16_t* Bt, int K, int ld, int ncolt  , const Epi& E, int first, int nblk, int bid, int tid) {
;     ...
;     for (int u = ub; u < 8 * ncolt; u += nblk) {
;         const int rt = u & 7, ct = u >> 3;
;         const int row0 = NPT + 64 * rt, col0 = NC * ct;
;         u32x4 ra[2][4], rb[2][4];
;     ...
;         SG_LOAD(0, 0); SG_LOAD(1, 1);
;         f32x4 acc0 = {0.f, 0.f, 0.f, 0.f}, acc1 = {0.f, 0.f, 0.f, 0.f};
;         const LAS unsigned char* apl = lds + (16 * mt + fr) * SG_STRIDE + 16 * fq;
;         const LAS unsigned char* bpl = lds + SG_BOFF + ((NC / 2) * nh + fr) * SG_STRIDE + 16 * fq;
; #pragma unroll 1
;         for (int kc = 0; kc < nch; kc += 2) { SG_STEP(kc, 0); SG_STEP(kc + 1, 1); }
.LBB0_812:
	s_lshl_b32 s10, s3, 6
	s_and_b32 s13, s10, 0x1c0
	s_bitset1_b32 s13, 14
	s_lshl_b32 s10, s3, 2
	v_or_b32_e32 v0, s13, v180
	s_and_b32 s12, s10, 0x7fffffe0
	v_lshlrev_b32_e32 v52, 11, v0
	v_lshl_add_u64 v[58:59], v[54:55], 0, v[52:53]
	v_or_b32_e32 v52, s12, v180
	v_lshlrev_b64 v[0:1], 11, v[52:53]
	v_lshl_add_u64 v[60:61], v[56:57], 0, v[0:1]
	v_or_b32_e32 v0, s13, v79
	v_lshlrev_b32_e32 v52, 11, v0
	v_lshl_add_u64 v[62:63], v[54:55], 0, v[52:53]
	v_add_u32_e32 v52, s12, v79
	v_lshlrev_b64 v[0:1], 11, v[52:53]
	v_lshl_add_u64 v[64:65], v[56:57], 0, v[0:1]
	v_or_b32_e32 v0, s13, v80
	v_lshlrev_b32_e32 v52, 11, v0
	v_lshl_add_u64 v[66:67], v[54:55], 0, v[52:53]
	v_add_lshl_u32 v52, s13, v81, 11
	v_lshl_add_u64 v[68:69], v[54:55], 0, v[52:53]
	global_load_dwordx4 v[0:3], v[58:59], off
	global_load_dwordx4 v[4:7], v[58:59], off offset:512
	global_load_dwordx4 v[8:11], v[60:61], off
	global_load_dwordx4 v[12:15], v[60:61], off offset:512
	global_load_dwordx4 v[16:19], v[62:63], off
	global_load_dwordx4 v[20:23], v[62:63], off offset:512
	global_load_dwordx4 v[24:27], v[64:65], off
	global_load_dwordx4 v[28:31], v[64:65], off offset:512
	global_load_dwordx4 v[32:35], v[66:67], off
	global_load_dwordx4 v[36:39], v[66:67], off offset:512
	global_load_dwordx4 v[40:43], v[68:69], off
	global_load_dwordx4 v[44:47], v[68:69], off offset:512
	s_mov_b64 s[10:11], -1
	v_mov_b32_e32 v48, 0
	v_mov_b32_e32 v49, v53
	v_mov_b32_e32 v50, v53
	v_mov_b32_e32 v51, v53
	v_and_b32_e32 v138, 15, v192
	v_mul_u32_u24_e32 v138, 0x210, v138
	v_bfe_u32 v139, v192, 4, 2
	v_lshl_add_u32 v138, v139, 4, v138
	v_lshrrev_b32_e32 v139, 6, v192
	v_lshl_add_u32 v138, v139, 6, v138
	v_add_u32_e32 v139, 0x10800, v138
	v_mov_b32_e32 v106, 0
	v_mov_b32_e32 v107, 0
	v_mov_b32_e32 v108, 0
	v_mov_b32_e32 v109, 0
	v_mov_b32_e32 v110, 0
	v_mov_b32_e32 v111, 0
	v_mov_b32_e32 v112, 0
	v_mov_b32_e32 v113, 0
	v_mov_b32_e32 v114, 0
	v_mov_b32_e32 v115, 0
	v_mov_b32_e32 v116, 0
	v_mov_b32_e32 v117, 0
	v_mov_b32_e32 v118, 0
	v_mov_b32_e32 v119, 0
	v_mov_b32_e32 v120, 0
	v_mov_b32_e32 v121, 0
	v_mov_b32_e32 v122, 0
	v_mov_b32_e32 v123, 0
	v_mov_b32_e32 v124, 0
	v_mov_b32_e32 v125, 0
	v_mov_b32_e32 v126, 0
	v_mov_b32_e32 v127, 0
	v_mov_b32_e32 v128, 0
	v_mov_b32_e32 v129, 0
	v_mov_b32_e32 v130, 0
	v_mov_b32_e32 v131, 0
	v_mov_b32_e32 v132, 0
	v_mov_b32_e32 v133, 0
	v_mov_b32_e32 v134, 0
	v_mov_b32_e32 v135, 0
	v_mov_b32_e32 v136, 0
	v_mov_b32_e32 v137, 0
	s_branch .LBB0_814
.LBB0_813:
	s_waitcnt lgkmcnt(0)
	s_barrier
	ds_read_b128 v[194:197], v139
	ds_read_b128 v[198:201], v139 offset:8448
	ds_read_b128 v[202:205], v139 offset:16896
	ds_read_b128 v[206:209], v139 offset:25344
	ds_read_b128 v[210:213], v139 offset:33792
	ds_read_b128 v[214:217], v139 offset:42240
	s_waitcnt lgkmcnt(0)
	v_mfma_f32_16x16x32_bf16 v[106:109], v[210:213], v[194:197], v[106:109]
	v_mfma_f32_16x16x32_bf16 v[110:113], v[214:217], v[194:197], v[110:113]
	v_mfma_f32_16x16x32_bf16 v[114:117], v[210:213], v[198:201], v[114:117]
	v_mfma_f32_16x16x32_bf16 v[118:121], v[214:217], v[198:201], v[118:121]
	v_mfma_f32_16x16x32_bf16 v[122:125], v[210:213], v[202:205], v[122:125]
	v_mfma_f32_16x16x32_bf16 v[126:129], v[214:217], v[202:205], v[126:129]
	v_mfma_f32_16x16x32_bf16 v[130:133], v[210:213], v[206:209], v[130:133]
	v_mfma_f32_16x16x32_bf16 v[134:137], v[214:217], v[206:209], v[134:137]
	s_xor_b64 s[14:15], s[10:11], -1
	s_mov_b64 s[10:11], 0
	s_and_b64 vcc, exec, s[14:15]
	s_cbranch_vccnz .Lsk_p4_reduce

.LBB0_816:
	s_waitcnt lgkmcnt(0)
	s_barrier
	ds_read_b128 v[194:197], v138
	ds_read_b128 v[198:201], v138 offset:8448
	ds_read_b128 v[202:205], v138 offset:16896
	ds_read_b128 v[206:209], v138 offset:25344
	ds_read_b128 v[210:213], v138 offset:33792
	ds_read_b128 v[214:217], v138 offset:42240
	s_waitcnt lgkmcnt(0)
	v_mfma_f32_16x16x32_bf16 v[106:109], v[210:213], v[194:197], v[106:109]
	v_mfma_f32_16x16x32_bf16 v[110:113], v[214:217], v[194:197], v[110:113]
	v_mfma_f32_16x16x32_bf16 v[114:117], v[210:213], v[198:201], v[114:117]
	v_mfma_f32_16x16x32_bf16 v[118:121], v[214:217], v[198:201], v[118:121]
	v_mfma_f32_16x16x32_bf16 v[122:125], v[210:213], v[202:205], v[122:125]
	v_mfma_f32_16x16x32_bf16 v[126:129], v[214:217], v[202:205], v[126:129]
	v_mfma_f32_16x16x32_bf16 v[130:133], v[210:213], v[206:209], v[130:133]
	v_mfma_f32_16x16x32_bf16 v[134:137], v[214:217], v[206:209], v[134:137]
	v_add_u32_e32 v99, v75, v82
	v_add_u32_e32 v52, v74, v82
	s_andn2_b64 vcc, exec, s[10:11]
	ds_write_b128 v99, v[12:15]
	v_add_u32_e32 v99, v74, v83
	ds_write_b128 v52, v[4:7]
	ds_write_b128 v99, v[20:23]
	v_add_u32_e32 v99, v75, v83
	ds_write_b128 v99, v[28:31]
	ds_write_b128 v52, v[36:39] offset:16896
	v_add_u32_e32 v52, v74, v84
	s_waitcnt vmcnt(0)
	ds_write_b128 v52, v[44:47]
	s_cbranch_vccnz .LBB0_813
	global_load_dwordx4 v[4:7], v[58:59], off offset:1536
	global_load_dwordx4 v[12:15], v[60:61], off offset:1536
	global_load_dwordx4 v[20:23], v[62:63], off offset:1536
	global_load_dwordx4 v[28:31], v[64:65], off offset:1536
	global_load_dwordx4 v[36:39], v[66:67], off offset:1536
	global_load_dwordx4 v[44:47], v[68:69], off offset:1536
	s_branch .LBB0_813

; #define LAS __attribute__((address_space(3)))
; #define SG_LOAD(kc, sg) do { _Pragma("unroll") for (int i_ = 0; i_ < 4; ++i_) { const int idx_ = tid + 512 * i_; \
;             ra[sg][i_] = *(const u32x4*)(A + (size_t)(row0 + (idx_ >> 5)) * ld + (kc) * 256 + (idx_ & 31) * 8); if (NC == 64 || i_ < 2) rb[sg][i_] = *(const u32x4*)(Bt + (size_t)(col0 + (idx_ >> 5)) * ld + (kc) * 256 + (idx_ & 31) * 8); } } while (0)
; template <int NC, class Epi>
; __device__ __forceinline__ void small_gemm_phase(LAS unsigned char* lds, const bf16_t* A, const bf16_t* Bt, int K, int ld, int ncolt  , const Epi& E, int first, int nblk, int bid, int tid) {
;     ...
;     for (int u = ub; u < 8 * ncolt; u += nblk) {
;         const int rt = u & 7, ct = u >> 3;
;         const int row0 = NPT + 64 * rt, col0 = NC * ct;
;         u32x4 ra[2][4], rb[2][4];
;     ...
;         SG_LOAD(0, 0); SG_LOAD(1, 1);
;         f32x4 acc0 = {0.f, 0.f, 0.f, 0.f}, acc1 = {0.f, 0.f, 0.f, 0.f};
;         const LAS unsigned char* apl = lds + (16 * mt + fr) * SG_STRIDE + 16 * fq;
;         const LAS unsigned char* bpl = lds + SG_BOFF + ((NC / 2) * nh + fr) * SG_STRIDE + 16 * fq;
; #pragma unroll 1
;         for (int kc = 0; kc < nch; kc += 2) { SG_STEP(kc, 0); SG_STEP(kc + 1, 1); }
.LBB0_1039:
	s_lshl_b32 s12, s11, 6
	s_and_b32 s15, s12, 0x1c0
	s_bitset1_b32 s15, 14
	s_lshl_b32 s12, s11, 2
	v_or_b32_e32 v0, s15, v182
	s_and_b32 s14, s12, 0x7fffffe0
	v_lshlrev_b32_e32 v52, 11, v0
	v_lshl_add_u64 v[58:59], v[54:55], 0, v[52:53]
	v_or_b32_e32 v52, s14, v182
	v_lshlrev_b64 v[0:1], 11, v[52:53]
	v_lshl_add_u64 v[60:61], v[56:57], 0, v[0:1]
	v_or_b32_e32 v0, s15, v79
	v_lshlrev_b32_e32 v52, 11, v0
	v_lshl_add_u64 v[62:63], v[54:55], 0, v[52:53]
	v_add_u32_e32 v52, s14, v79
	v_lshlrev_b64 v[0:1], 11, v[52:53]
	v_lshl_add_u64 v[64:65], v[56:57], 0, v[0:1]
	v_or_b32_e32 v0, s15, v80
	v_lshlrev_b32_e32 v52, 11, v0
	v_lshl_add_u64 v[66:67], v[54:55], 0, v[52:53]
	v_add_lshl_u32 v52, s15, v81, 11
	v_lshl_add_u64 v[68:69], v[54:55], 0, v[52:53]
	s_waitcnt lgkmcnt(1)
	global_load_dwordx4 v[0:3], v[58:59], off
	s_waitcnt lgkmcnt(0)
	global_load_dwordx4 v[4:7], v[58:59], off offset:512
	global_load_dwordx4 v[8:11], v[60:61], off
	global_load_dwordx4 v[12:15], v[60:61], off offset:512
	global_load_dwordx4 v[16:19], v[62:63], off
	global_load_dwordx4 v[20:23], v[62:63], off offset:512
	global_load_dwordx4 v[24:27], v[64:65], off
	global_load_dwordx4 v[28:31], v[64:65], off offset:512
	global_load_dwordx4 v[32:35], v[66:67], off
	global_load_dwordx4 v[36:39], v[66:67], off offset:512
	global_load_dwordx4 v[40:43], v[68:69], off
	global_load_dwordx4 v[44:47], v[68:69], off offset:512
	s_mov_b64 s[12:13], -1
	v_mov_b32_e32 v48, 0
	v_mov_b32_e32 v49, v53
	v_mov_b32_e32 v50, v53
	v_mov_b32_e32 v51, v53
	v_and_b32_e32 v138, 15, v192
	v_mul_u32_u24_e32 v138, 0x210, v138
	v_bfe_u32 v139, v192, 4, 2
	v_lshl_add_u32 v138, v139, 4, v138
	v_lshrrev_b32_e32 v139, 6, v192
	v_lshl_add_u32 v138, v139, 6, v138
	v_add_u32_e32 v139, 0x10800, v138
	v_mov_b32_e32 v106, 0
	v_mov_b32_e32 v107, 0
	v_mov_b32_e32 v108, 0
	v_mov_b32_e32 v109, 0
	v_mov_b32_e32 v110, 0
	v_mov_b32_e32 v111, 0
	v_mov_b32_e32 v112, 0
	v_mov_b32_e32 v113, 0
	v_mov_b32_e32 v114, 0
	v_mov_b32_e32 v115, 0
	v_mov_b32_e32 v116, 0
	v_mov_b32_e32 v117, 0
	v_mov_b32_e32 v118, 0
	v_mov_b32_e32 v119, 0
	v_mov_b32_e32 v120, 0
	v_mov_b32_e32 v121, 0
	v_mov_b32_e32 v122, 0
	v_mov_b32_e32 v123, 0
	v_mov_b32_e32 v124, 0
	v_mov_b32_e32 v125, 0
	v_mov_b32_e32 v126, 0
	v_mov_b32_e32 v127, 0
	v_mov_b32_e32 v128, 0
	v_mov_b32_e32 v129, 0
	v_mov_b32_e32 v130, 0
	v_mov_b32_e32 v131, 0
	v_mov_b32_e32 v132, 0
	v_mov_b32_e32 v133, 0
	v_mov_b32_e32 v134, 0
	v_mov_b32_e32 v135, 0
	v_mov_b32_e32 v136, 0
	v_mov_b32_e32 v137, 0
	s_branch .LBB0_1041
.LBB0_1040:
	s_waitcnt lgkmcnt(0)
	s_barrier
	ds_read_b128 v[194:197], v139
	ds_read_b128 v[198:201], v139 offset:8448
	ds_read_b128 v[202:205], v139 offset:16896
	ds_read_b128 v[206:209], v139 offset:25344
	ds_read_b128 v[210:213], v139 offset:33792
	ds_read_b128 v[214:217], v139 offset:42240
	s_waitcnt lgkmcnt(0)
	v_mfma_f32_16x16x32_bf16 v[106:109], v[210:213], v[194:197], v[106:109]
	v_mfma_f32_16x16x32_bf16 v[110:113], v[214:217], v[194:197], v[110:113]
	v_mfma_f32_16x16x32_bf16 v[114:117], v[210:213], v[198:201], v[114:117]
	v_mfma_f32_16x16x32_bf16 v[118:121], v[214:217], v[198:201], v[118:121]
	v_mfma_f32_16x16x32_bf16 v[122:125], v[210:213], v[202:205], v[122:125]
	v_mfma_f32_16x16x32_bf16 v[126:129], v[214:217], v[202:205], v[126:129]
	v_mfma_f32_16x16x32_bf16 v[130:133], v[210:213], v[206:209], v[130:133]
	v_mfma_f32_16x16x32_bf16 v[134:137], v[214:217], v[206:209], v[134:137]
	s_xor_b64 s[16:17], s[12:13], -1
	s_mov_b64 s[12:13], 0
	s_and_b64 vcc, exec, s[16:17]
	s_cbranch_vccnz .Lsk_p6_reduce

.LBB0_1043:
	s_waitcnt lgkmcnt(0)
	s_barrier
	ds_read_b128 v[194:197], v138
	ds_read_b128 v[198:201], v138 offset:8448
	ds_read_b128 v[202:205], v138 offset:16896
	ds_read_b128 v[206:209], v138 offset:25344
	ds_read_b128 v[210:213], v138 offset:33792
	ds_read_b128 v[214:217], v138 offset:42240
	s_waitcnt lgkmcnt(0)
	v_mfma_f32_16x16x32_bf16 v[106:109], v[210:213], v[194:197], v[106:109]
	v_mfma_f32_16x16x32_bf16 v[110:113], v[214:217], v[194:197], v[110:113]
	v_mfma_f32_16x16x32_bf16 v[114:117], v[210:213], v[198:201], v[114:117]
	v_mfma_f32_16x16x32_bf16 v[118:121], v[214:217], v[198:201], v[118:121]
	v_mfma_f32_16x16x32_bf16 v[122:125], v[210:213], v[202:205], v[122:125]
	v_mfma_f32_16x16x32_bf16 v[126:129], v[214:217], v[202:205], v[126:129]
	v_mfma_f32_16x16x32_bf16 v[130:133], v[210:213], v[206:209], v[130:133]
	v_mfma_f32_16x16x32_bf16 v[134:137], v[214:217], v[206:209], v[134:137]
	v_add_u32_e32 v52, v74, v82
	s_andn2_b64 vcc, exec, s[12:13]
	ds_write_b128 v52, v[4:7]
	v_add_u32_e32 v104, v75, v82
	ds_write_b128 v104, v[12:15]
	v_add_u32_e32 v104, v74, v83
	ds_write_b128 v104, v[20:23]
	v_add_u32_e32 v104, v75, v83
	ds_write_b128 v104, v[28:31]
	ds_write_b128 v52, v[36:39] offset:16896
	v_add_u32_e32 v52, v74, v84
	s_waitcnt vmcnt(0)
	ds_write_b128 v52, v[44:47]
	s_cbranch_vccnz .LBB0_1040
	global_load_dwordx4 v[4:7], v[58:59], off offset:1536
	global_load_dwordx4 v[12:15], v[60:61], off offset:1536
	global_load_dwordx4 v[20:23], v[62:63], off offset:1536
	global_load_dwordx4 v[28:31], v[64:65], off offset:1536
	global_load_dwordx4 v[36:39], v[66:67], off offset:1536
	global_load_dwordx4 v[44:47], v[68:69], off offset:1536
	s_branch .LBB0_1040
